# P0 conversion items split unequally: workgroups that run the modulation GEMV take 8 items per wave, the others 34
# speedup vs baseline: 1.0102x; 1.0102x over previous
.LBB0_44:
	s_or_b64 exec, exec, s[0:1]
	s_mov_b32 s97, s38
	s_lshl_b32 s0, s38, 3
	s_add_i32 s22, s0, s20
	s_cmpk_lt_u32 s38, 144
	s_cbranch_scc1 .Lcv_mod
	s_addk_i32 s22, -1152
	s_movk_i32 s98, 896
	s_mov_b32 s99, 30783
	s_branch .Lcv_go
.Lcv_mod:
	s_add_i32 s22, s22, 30784
	s_movk_i32 s98, 1152
	s_mov_b32 s99, 0x9c3f
.Lcv_go:
	s_cmp_gt_i32 s22, s99
	s_cbranch_scc1 .LBB0_116
	s_lshl_b32 s0, s20, 14
	v_lshrrev_b32_e32 v3, 5, v93
	v_and_b32_e32 v0, 31, v181
	s_add_i32 s0, s0, 0
	v_lshlrev_b32_e32 v2, 2, v0
	v_mul_u32_u24_e32 v4, 0x84, v3
	v_add3_u32 v6, s0, v2, v4
	v_and_b32_e32 v4, 7, v181
	v_lshrrev_b32_e32 v7, 3, v93
	v_lshlrev_b32_e32 v2, 3, v4
	v_mul_u32_u24_e32 v4, 0x420, v4
	v_lshlrev_b32_e32 v5, 2, v7
	v_mov_b32_e32 v1, 0
	v_add3_u32 v8, s0, v4, v5
	v_or_b32_e32 v9, 8, v7
	v_or_b32_e32 v10, 16, v7
	v_or_b32_e32 v11, 24, v7
	v_mov_b32_e32 v12, 0x23fb0
	v_mov_b32_e32 v13, 0x23fb4
	v_mov_b32_e32 v14, 0x23f88
	v_mov_b32_e32 v15, 0x23f8c
	v_mov_b32_e32 v16, 0x23f80
	v_mov_b32_e32 v17, 0x23f84
	s_movk_i32 s23, 0x4000
	s_mov_b32 s24, 0x8000
	s_mov_b32 s25, 0xc000
	s_mov_b32 s26, 0x10000
	s_mov_b32 s27, 0x14000
	s_mov_b32 s28, 0x18000
	s_mov_b32 s29, 0x1c000
	s_mov_b32 s30, 0x20000
	s_mov_b32 s31, 0x24000
	s_mov_b32 s34, 0x28000
	s_mov_b32 s35, 0x2c000
	s_mov_b32 s36, 0x30000
	s_mov_b32 s37, 0x34000
	s_mov_b32 s38, 0x38000
	s_mov_b32 s39, 0x3c000
	s_mov_b32 s40, 0x48000
	s_mov_b32 s41, 0x54000
	s_mov_b32 s42, 0x58000
	s_mov_b32 s43, 0x60000
	s_mov_b32 s44, 0x68000
	s_mov_b32 s45, 0x6c000
	s_mov_b32 s46, 0x78000
	v_mov_b32_e32 v18, 0x23f78
	v_mov_b32_e32 v19, 0x23f7c
	v_mov_b32_e32 v20, 0x23f70
	v_mov_b32_e32 v21, 0x23f74
	s_movk_i32 s47, 0x3000
	s_movk_i32 s48, 0x6000
	s_mov_b32 s49, 0x9000
	s_mov_b32 s50, 0xf000
	s_mov_b32 s51, 0x12000
	s_mov_b32 s52, 0x15000
	s_mov_b32 s53, 0x1b000
	s_mov_b32 s54, 0x1e000
	s_mov_b32 s55, 0x21000
	s_mov_b32 s56, 0x2a000
	s_mov_b32 s57, 0x36000
	s_mov_b32 s58, 0x42000
	s_mov_b32 s59, 0x4e000
	s_mov_b32 s60, 0x5a000
	s_mov_b32 s61, 0x5d000
	v_mov_b32_e32 v22, 0x23f68
	v_mov_b32_e32 v23, 0x23f6c
	s_movk_i32 s62, 0x2000
	s_movk_i32 s63, 0x5000
	s_mov_b32 s64, 0xa000
	s_mov_b32 s65, 0xb000
	s_mov_b32 s66, 0xe000
	s_mov_b32 s67, 0x16000
	s_mov_b32 s68, 0x1a000
	v_mov_b32_e32 v24, 0x23fa0
	v_mov_b32_e32 v25, 0x23fa4
	s_mov_b32 s69, 0x22000
	s_mov_b32 s70, 0x26000
	s_mov_b32 s71, 0x2e000
	s_mov_b32 s72, 0x32000
	s_mov_b32 s73, 0x3a000
	s_mov_b32 s74, 0x3e000
	v_mov_b32_e32 v26, 0x23f60
	v_mov_b32_e32 v27, 0x23f64
	v_mov_b32_e32 v28, 0x23f50
	v_mov_b32_e32 v29, 0x23f54
	s_mov_b32 s75, 0x7e000
	s_mov_b32 s76, 0x84000
	v_mov_b32_e32 v30, 0x23f48
	v_mov_b32_e32 v31, 0x23f4c
	v_mov_b32_e32 v32, 0x23f40
	v_mov_b32_e32 v33, 0x23f44
	s_mov_b32 s77, 0x31000
	s_mov_b32 s78, 0x37000
	s_mov_b32 s79, 0x47000
	s_mov_b32 s80, 0x4d000
	s_mov_b32 s81, 0x52000
	s_mov_b32 s82, 0x63000
	s_mov_b32 s83, 0x6e000
	v_mov_b32_e32 v34, 0x23f38
	v_mov_b32_e32 v35, 0x23f3c
	v_lshlrev_b32_e32 v0, 2, v0
	v_add_u32_e32 v36, 0x400, v6
	v_add_u32_e32 v37, 0x800, v6
	v_add_u32_e32 v38, 0xc00, v6
	v_add_u32_e32 v39, 0x1000, v6
	v_add_u32_e32 v40, 0x1400, v6
	v_add_u32_e32 v41, 0x1800, v6
	v_add_u32_e32 v42, 0x1c00, v6
	s_mov_b32 s84, 0x73000
	s_mov_b32 s85, 0x79000
	s_mov_b32 s86, 0x89000
	s_mov_b32 s87, 0x8f000
	s_mov_b32 s88, 0x94000
	s_mov_b32 s89, 0x9a000
	s_mov_b32 s90, 0x9f000
	s_mov_b32 s91, 0xa5000
	s_mov_b32 s92, 0xaa000
	s_mov_b32 s3, 0
	s_mov_b64 s[4:5], 0x9c00000
	s_mov_b64 s[6:7], 0xa200000
	s_mov_b64 s[8:9], 0x9800000
	s_mov_b64 s[10:11], 0x8c00000
	s_mov_b64 s[12:13], 0x6000000
	s_mov_b64 s[14:15], 0x800000
	s_branch .LBB0_47
.LBB0_46:
	v_readlane_b32 s0, v255, 2
	s_lshl_b32 s0, s0, 3
	s_add_i32 s22, s98, s22
	s_cmp_gt_i32 s22, s99
	v_readlane_b32 s1, v255, 3
	s_cbranch_scc1 .LBB0_116
